# v181 with the P4 epilogue x loads issued without the nt hint
# baseline (speedup 1.0000x reference)
; __device__ __forceinline__ u32x4 pack8(const float (&f)[8]) { u32x4 w; w.x = cvt_pk_bf16(f[0], f[1]); w.y = cvt_pk_bf16(f[2], f[3]); w.z = cvt_pk_bf16(f[4], f[5]); w.w = cvt_pk_bf16(f[6], f[7]); return w; }
;     __device__ __forceinline__ void operator()(const f32x4 (&acc)[2][2][4][2], const Unit& u, int wr, int wc, int fr, int fq) const {
;         const int row0 = u.pm * BM + wr * 64 + fr, col0 = u.pn * BM + wc * 32 + 8 * fq;
; #pragma unroll
;         for (int ai = 0; ai < 2; ++ai)
; #pragma unroll
;             for (int m = 0; m < 4; ++m) { const int row = row0 + ai * HALF + m * 16; const size_t idx = (size_t)row * 1024 + col0; float ss = 0.f;
; #pragma unroll
;                 for (int bj = 0; bj < 2; ++bj) { const f32x4 x0 = __builtin_nontemporal_load((const f32x4*)(x + idx + bj * HALF)), x1 = __builtin_nontemporal_load((const f32x4*)(x + idx + bj * HALF + 4));
;                     const f32x4 h0 = x0 + acc[ai][bj][m][0], h1v = x1 + acc[ai][bj][m][1];
;                     float f[8] = {h0[0], h0[1], h0[2], h0[3], h1v[0], h1v[1], h1v[2], h1v[3]};
; #pragma unroll
;                     for (int e = 0; e < 8; ++e) ss += f[e] * f[e];
;                     *(u32x4*)(h1b + idx + bj * HALF) = pack8(f); }
;                 ss += __shfl_xor(ss, 16); ss += __shfl_xor(ss, 32);
;                 if (fq == 0) atomicAdd(ssq + row, ss); }
.LBB0_648:
	v_lshl_add_u32 v148, s44, 8, v150
	v_lshlrev_b32_e32 v149, 2, v148
	v_bfe_u32 v236, v150, 6, 1
	v_bfe_u32 v237, v152, 5, 2
	v_lshl_or_b32 v236, v236, 2, v237
	v_mul_u32_u24_e32 v236, 0x500, v236
	v_add_u32_e32 v236, 0x20000, v236
	v_and_b32_e32 v237, 7, v150
	v_bfe_u32 v238, v152, 3, 2
	v_lshlrev_b32_e32 v238, 1, v238
	v_xor_b32_e32 v239, v238, v237
	v_lshlrev_b32_e32 v239, 4, v239
	v_lshl_add_u32 v227, v237, 7, v239
	v_add_u32_e32 v227, v227, v236
	v_or_b32_e32 v238, 1, v238
	v_xor_b32_e32 v239, v238, v237
	v_lshlrev_b32_e32 v239, 4, v239
	v_lshl_add_u32 v228, v237, 7, v239
	v_add_u32_e32 v228, v228, v236
	v_lshrrev_b32_e32 v237, 3, v156
	v_and_b32_e32 v238, 7, v156
	v_xor_b32_e32 v239, v238, v237
	v_lshlrev_b32_e32 v239, 4, v239
	v_lshl_add_u32 v226, v237, 7, v239
	v_add_u32_e32 v226, v226, v236
	v_and_or_b32 v147, v150, -16, v237
	v_lshl_add_u32 v147, s44, 8, v147
	v_and_b32_e32 v239, 0xffffffe7, v152
	v_lshl_or_b32 v239, s46, 8, v239
	v_lshl_add_u32 v239, v238, 2, v239
	v_lshl_add_u32 v147, v147, 10, v239
	v_lshlrev_b32_e32 v147, 2, v147
	v_add_u32_e32 v144, 0x8000, v147
	v_and_b32_e32 v237, 15, v150
	v_mul_u32_u24_e32 v234, 0x50, v237
	v_bfe_u32 v238, v152, 3, 2
	v_lshl_add_u32 v234, v238, 4, v234
	v_add_u32_e32 v234, v234, v236
	v_lshrrev_b32_e32 v237, 2, v156
	v_and_b32_e32 v238, 3, v156
	v_mul_u32_u24_e32 v235, 0x50, v237
	v_lshl_add_u32 v235, v238, 4, v235
	v_add_u32_e32 v235, v235, v236
	v_and_or_b32 v145, v150, -16, v237
	v_lshl_add_u32 v145, s44, 8, v145
	v_and_b32_e32 v239, 0xffffffe7, v152
	v_lshl_or_b32 v239, s46, 8, v239
	v_lshl_add_u32 v239, v238, 3, v239
	v_lshl_add_u32 v145, v145, 10, v239
	v_lshlrev_b32_e32 v145, 1, v145
	s_mov_b32 s98, 0x00ff00ff
	s_mov_b32 s99, 0x00ff00ff
	s_mov_b32 s100, 0xff00ff00
	s_mov_b32 s101, 0xff00ff00
	global_load_dwordx4 v[158:161], v147, s[52:53]
	global_load_dwordx4 v[162:165], v144, s[52:53]
	global_load_dwordx4 v[166:169], v147, s[52:53] offset:512
	global_load_dwordx4 v[170:173], v144, s[52:53] offset:512
	v_add_u32_e32 v147, 0x10000, v147
	v_add_u32_e32 v144, 0x10000, v144
	global_load_dwordx4 v[174:177], v147, s[52:53]
	global_load_dwordx4 v[178:181], v144, s[52:53]
	global_load_dwordx4 v[182:185], v147, s[52:53] offset:512
	global_load_dwordx4 v[186:189], v144, s[52:53] offset:512
	v_add_u32_e32 v147, 0x10000, v147
	v_add_u32_e32 v144, 0x10000, v144
	global_load_dwordx4 v[190:193], v147, s[52:53]
	global_load_dwordx4 v[194:197], v144, s[52:53]
	global_load_dwordx4 v[198:201], v147, s[52:53] offset:512
	global_load_dwordx4 v[206:209], v144, s[52:53] offset:512
	v_add_u32_e32 v147, 0x10000, v147
	v_add_u32_e32 v144, 0x10000, v144
	global_load_dwordx4 v[210:213], v147, s[52:53]
	global_load_dwordx4 v[214:217], v144, s[52:53]
	global_load_dwordx4 v[218:221], v147, s[52:53] offset:512
	global_load_dwordx4 v[222:225], v144, s[52:53] offset:512
	v_add_u32_e32 v147, 0x50000, v147
	v_add_u32_e32 v144, 0x50000, v144
	s_waitcnt vmcnt(12)
	ds_write_b128 v226, v[158:161]
	s_mov_b64 exec, s[98:99]
	ds_read_b128 v[158:161], v227
	ds_read_b128 v[230:233], v228
	s_mov_b64 exec, -1
	ds_write_b128 v226, v[162:165]
	s_mov_b64 exec, s[100:101]
	ds_read_b128 v[158:161], v227
	ds_read_b128 v[230:233], v228
	s_mov_b64 exec, -1
	s_waitcnt lgkmcnt(0)
	v_pk_add_f32 v[124:125], v[124:125], v[158:159]
	v_pk_add_f32 v[126:127], v[126:127], v[160:161]
	v_pk_add_f32 v[120:121], v[120:121], v[230:231]
	v_pk_add_f32 v[122:123], v[122:123], v[232:233]
	ds_write_b128 v226, v[166:169]
	s_mov_b64 exec, s[98:99]
	ds_read_b128 v[166:169], v227
	ds_read_b128 v[230:233], v228
	s_mov_b64 exec, -1
	ds_write_b128 v226, v[170:173]
	s_mov_b64 exec, s[100:101]
	ds_read_b128 v[166:169], v227
	ds_read_b128 v[230:233], v228
	s_mov_b64 exec, -1
	s_waitcnt lgkmcnt(0)
	v_pk_add_f32 v[116:117], v[116:117], v[166:167]
	v_pk_add_f32 v[118:119], v[118:119], v[168:169]
	v_pk_add_f32 v[112:113], v[112:113], v[230:231]
	v_pk_add_f32 v[114:115], v[114:115], v[232:233]
	v_cvt_pk_bf16_f32 v158, v124, v125
	v_cvt_pk_bf16_f32 v159, v126, v127
	v_cvt_pk_bf16_f32 v160, v120, v121
	v_cvt_pk_bf16_f32 v161, v122, v123
	v_cvt_pk_bf16_f32 v166, v116, v117
	v_cvt_pk_bf16_f32 v167, v118, v119
	v_cvt_pk_bf16_f32 v168, v112, v113
	v_cvt_pk_bf16_f32 v169, v114, v115
	ds_write_b128 v234, v[158:161]
	ds_read_b128 v[158:161], v235
	ds_write_b128 v234, v[166:169]
	ds_read_b128 v[166:169], v235
	v_mul_f32_e32 v157, v124, v124
	v_fmac_f32_e32 v157, v125, v125
	v_fmac_f32_e32 v157, v126, v126
	v_fmac_f32_e32 v157, v127, v127
	v_fmac_f32_e32 v157, v120, v120
	v_fmac_f32_e32 v157, v121, v121
	v_fmac_f32_e32 v157, v122, v122
	v_fmac_f32_e32 v157, v123, v123
	v_fmac_f32_e32 v157, v116, v116
	v_fmac_f32_e32 v157, v117, v117
	v_fmac_f32_e32 v157, v118, v118
	v_fmac_f32_e32 v157, v119, v119
	v_fmac_f32_e32 v157, v112, v112
	v_fmac_f32_e32 v157, v113, v113
	v_fmac_f32_e32 v157, v114, v114
	v_fmac_f32_e32 v157, v115, v115
	s_waitcnt lgkmcnt(2)
	global_store_dwordx4 v145, v[158:161], s[8:9]
	s_waitcnt lgkmcnt(0)
	global_store_dwordx4 v145, v[166:169], s[8:9] offset:256
	v_add_u32_e32 v145, 0x8000, v145
	global_load_dwordx4 v[158:161], v147, s[52:53]
	global_load_dwordx4 v[162:165], v144, s[52:53]
	global_load_dwordx4 v[166:169], v147, s[52:53] offset:512
	global_load_dwordx4 v[170:173], v144, s[52:53] offset:512
	v_add_u32_e32 v147, 0x10000, v147
	v_add_u32_e32 v144, 0x10000, v144
	s_waitcnt vmcnt(14)
	ds_write_b128 v226, v[174:177]
	s_mov_b64 exec, s[98:99]
	ds_read_b128 v[174:177], v227
	ds_read_b128 v[230:233], v228
	s_mov_b64 exec, -1
	ds_write_b128 v226, v[178:181]
	s_mov_b64 exec, s[100:101]
	ds_read_b128 v[174:177], v227
	ds_read_b128 v[230:233], v228
	s_mov_b64 exec, -1
	s_waitcnt lgkmcnt(0)
; __device__ __forceinline__ u32x4 pack8(const float (&f)[8]) { u32x4 w; w.x = cvt_pk_bf16(f[0], f[1]); w.y = cvt_pk_bf16(f[2], f[3]); w.z = cvt_pk_bf16(f[4], f[5]); w.w = cvt_pk_bf16(f[6], f[7]); return w; }
;     __device__ __forceinline__ void operator()(const f32x4 (&acc)[2][2][4][2], const Unit& u, int wr, int wc, int fr, int fq) const {
;         const int row0 = u.pm * BM + wr * 64 + fr, col0 = u.pn * BM + wc * 32 + 8 * fq;
; #pragma unroll
;         for (int ai = 0; ai < 2; ++ai)
; #pragma unroll
;             for (int m = 0; m < 4; ++m) { const int row = row0 + ai * HALF + m * 16; const size_t idx = (size_t)row * 1024 + col0; float ss = 0.f;
; #pragma unroll
;                 for (int bj = 0; bj < 2; ++bj) { const f32x4 x0 = __builtin_nontemporal_load((const f32x4*)(x + idx + bj * HALF)), x1 = __builtin_nontemporal_load((const f32x4*)(x + idx + bj * HALF + 4));
;                     const f32x4 h0 = x0 + acc[ai][bj][m][0], h1v = x1 + acc[ai][bj][m][1];
;                     float f[8] = {h0[0], h0[1], h0[2], h0[3], h1v[0], h1v[1], h1v[2], h1v[3]};
; #pragma unroll
;                     for (int e = 0; e < 8; ++e) ss += f[e] * f[e];
;                     *(u32x4*)(h1b + idx + bj * HALF) = pack8(f); }
;                 ss += __shfl_xor(ss, 16); ss += __shfl_xor(ss, 32);
;                 if (fq == 0) atomicAdd(ssq + row, ss); }
	v_pk_add_f32 v[108:109], v[108:109], v[174:175]
	v_pk_add_f32 v[110:111], v[110:111], v[176:177]
	v_pk_add_f32 v[104:105], v[104:105], v[230:231]
	v_pk_add_f32 v[106:107], v[106:107], v[232:233]
	ds_write_b128 v226, v[182:185]
	s_mov_b64 exec, s[98:99]
	ds_read_b128 v[182:185], v227
	ds_read_b128 v[230:233], v228
	s_mov_b64 exec, -1
	ds_write_b128 v226, v[186:189]
	s_mov_b64 exec, s[100:101]
	ds_read_b128 v[182:185], v227
	ds_read_b128 v[230:233], v228
	s_mov_b64 exec, -1
	s_waitcnt lgkmcnt(0)
	v_pk_add_f32 v[100:101], v[100:101], v[182:183]
	v_pk_add_f32 v[102:103], v[102:103], v[184:185]
	v_pk_add_f32 v[96:97], v[96:97], v[230:231]
	v_pk_add_f32 v[98:99], v[98:99], v[232:233]
	v_cvt_pk_bf16_f32 v174, v108, v109
	v_cvt_pk_bf16_f32 v175, v110, v111
	v_cvt_pk_bf16_f32 v176, v104, v105
	v_cvt_pk_bf16_f32 v177, v106, v107
	v_cvt_pk_bf16_f32 v182, v100, v101
	v_cvt_pk_bf16_f32 v183, v102, v103
	v_cvt_pk_bf16_f32 v184, v96, v97
	v_cvt_pk_bf16_f32 v185, v98, v99
	ds_write_b128 v234, v[174:177]
	ds_read_b128 v[174:177], v235
	ds_write_b128 v234, v[182:185]
	ds_read_b128 v[182:185], v235
	v_mul_f32_e32 v202, v108, v108
	v_fmac_f32_e32 v202, v109, v109
	v_fmac_f32_e32 v202, v110, v110
	v_fmac_f32_e32 v202, v111, v111
	v_fmac_f32_e32 v202, v104, v104
	v_fmac_f32_e32 v202, v105, v105
	v_fmac_f32_e32 v202, v106, v106
	v_fmac_f32_e32 v202, v107, v107
	v_fmac_f32_e32 v202, v100, v100
	v_fmac_f32_e32 v202, v101, v101
	v_fmac_f32_e32 v202, v102, v102
	v_fmac_f32_e32 v202, v103, v103
	v_fmac_f32_e32 v202, v96, v96
	v_fmac_f32_e32 v202, v97, v97
	v_fmac_f32_e32 v202, v98, v98
	v_fmac_f32_e32 v202, v99, v99
	s_waitcnt lgkmcnt(2)
	global_store_dwordx4 v145, v[174:177], s[8:9]
	s_waitcnt lgkmcnt(0)
	global_store_dwordx4 v145, v[182:185], s[8:9] offset:256
	v_add_u32_e32 v145, 0x8000, v145
	global_load_dwordx4 v[174:177], v147, s[52:53]
	global_load_dwordx4 v[178:181], v144, s[52:53]
	global_load_dwordx4 v[182:185], v147, s[52:53] offset:512
	global_load_dwordx4 v[186:189], v144, s[52:53] offset:512
	v_add_u32_e32 v147, 0x10000, v147
	v_add_u32_e32 v144, 0x10000, v144
	s_waitcnt vmcnt(16)
	ds_write_b128 v226, v[190:193]
	s_mov_b64 exec, s[98:99]
	ds_read_b128 v[190:193], v227
	ds_read_b128 v[230:233], v228
	s_mov_b64 exec, -1
	ds_write_b128 v226, v[194:197]
	s_mov_b64 exec, s[100:101]
	ds_read_b128 v[190:193], v227
	ds_read_b128 v[230:233], v228
	s_mov_b64 exec, -1
	s_waitcnt lgkmcnt(0)
	v_pk_add_f32 v[92:93], v[92:93], v[190:191]
	v_pk_add_f32 v[94:95], v[94:95], v[192:193]
	v_pk_add_f32 v[88:89], v[88:89], v[230:231]
	v_pk_add_f32 v[90:91], v[90:91], v[232:233]
	ds_write_b128 v226, v[198:201]
	s_mov_b64 exec, s[98:99]
	ds_read_b128 v[198:201], v227
	ds_read_b128 v[230:233], v228
	s_mov_b64 exec, -1
	ds_write_b128 v226, v[206:209]
	s_mov_b64 exec, s[100:101]
	ds_read_b128 v[198:201], v227
	ds_read_b128 v[230:233], v228
	s_mov_b64 exec, -1
	s_waitcnt lgkmcnt(0)
	v_pk_add_f32 v[84:85], v[84:85], v[198:199]
	v_pk_add_f32 v[86:87], v[86:87], v[200:201]
	v_pk_add_f32 v[80:81], v[80:81], v[230:231]
	v_pk_add_f32 v[82:83], v[82:83], v[232:233]
	v_cvt_pk_bf16_f32 v190, v92, v93
	v_cvt_pk_bf16_f32 v191, v94, v95
	v_cvt_pk_bf16_f32 v192, v88, v89
	v_cvt_pk_bf16_f32 v193, v90, v91
	v_cvt_pk_bf16_f32 v198, v84, v85
	v_cvt_pk_bf16_f32 v199, v86, v87
	v_cvt_pk_bf16_f32 v200, v80, v81
	v_cvt_pk_bf16_f32 v201, v82, v83
	ds_write_b128 v234, v[190:193]
	ds_read_b128 v[190:193], v235
	ds_write_b128 v234, v[198:201]
	ds_read_b128 v[198:201], v235
	v_mul_f32_e32 v203, v92, v92
	v_fmac_f32_e32 v203, v93, v93
	v_fmac_f32_e32 v203, v94, v94
	v_fmac_f32_e32 v203, v95, v95
	v_fmac_f32_e32 v203, v88, v88
	v_fmac_f32_e32 v203, v89, v89
	v_fmac_f32_e32 v203, v90, v90
	v_fmac_f32_e32 v203, v91, v91
	v_fmac_f32_e32 v203, v84, v84
	v_fmac_f32_e32 v203, v85, v85
	v_fmac_f32_e32 v203, v86, v86
	v_fmac_f32_e32 v203, v87, v87
	v_fmac_f32_e32 v203, v80, v80
	v_fmac_f32_e32 v203, v81, v81
	v_fmac_f32_e32 v203, v82, v82
	v_fmac_f32_e32 v203, v83, v83
	s_waitcnt lgkmcnt(2)
	global_store_dwordx4 v145, v[190:193], s[8:9]
	s_waitcnt lgkmcnt(0)
	global_store_dwordx4 v145, v[198:201], s[8:9] offset:256
	v_add_u32_e32 v145, 0x8000, v145
	global_load_dwordx4 v[190:193], v147, s[52:53]
	global_load_dwordx4 v[194:197], v144, s[52:53]
	global_load_dwordx4 v[198:201], v147, s[52:53] offset:512
	global_load_dwordx4 v[206:209], v144, s[52:53] offset:512
	v_add_u32_e32 v147, 0x10000, v147
	v_add_u32_e32 v144, 0x10000, v144
	s_waitcnt vmcnt(18)
	ds_write_b128 v226, v[210:213]
	s_mov_b64 exec, s[98:99]
	ds_read_b128 v[210:213], v227
	ds_read_b128 v[230:233], v228
	s_mov_b64 exec, -1
	ds_write_b128 v226, v[214:217]
	s_mov_b64 exec, s[100:101]
	ds_read_b128 v[210:213], v227
	ds_read_b128 v[230:233], v228
	s_mov_b64 exec, -1
	s_waitcnt lgkmcnt(0)
	v_pk_add_f32 v[76:77], v[76:77], v[210:211]
	v_pk_add_f32 v[78:79], v[78:79], v[212:213]
	v_pk_add_f32 v[72:73], v[72:73], v[230:231]
	v_pk_add_f32 v[74:75], v[74:75], v[232:233]
	ds_write_b128 v226, v[218:221]
	s_mov_b64 exec, s[98:99]
	ds_read_b128 v[218:221], v227
	ds_read_b128 v[230:233], v228
	s_mov_b64 exec, -1
	ds_write_b128 v226, v[222:225]
	s_mov_b64 exec, s[100:101]
	ds_read_b128 v[218:221], v227
	ds_read_b128 v[230:233], v228
	s_mov_b64 exec, -1
	s_waitcnt lgkmcnt(0)
; __device__ __forceinline__ u32x4 pack8(const float (&f)[8]) { u32x4 w; w.x = cvt_pk_bf16(f[0], f[1]); w.y = cvt_pk_bf16(f[2], f[3]); w.z = cvt_pk_bf16(f[4], f[5]); w.w = cvt_pk_bf16(f[6], f[7]); return w; }
;     __device__ __forceinline__ void operator()(const f32x4 (&acc)[2][2][4][2], const Unit& u, int wr, int wc, int fr, int fq) const {
;         const int row0 = u.pm * BM + wr * 64 + fr, col0 = u.pn * BM + wc * 32 + 8 * fq;
; #pragma unroll
;         for (int ai = 0; ai < 2; ++ai)
; #pragma unroll
;             for (int m = 0; m < 4; ++m) { const int row = row0 + ai * HALF + m * 16; const size_t idx = (size_t)row * 1024 + col0; float ss = 0.f;
; #pragma unroll
;                 for (int bj = 0; bj < 2; ++bj) { const f32x4 x0 = __builtin_nontemporal_load((const f32x4*)(x + idx + bj * HALF)), x1 = __builtin_nontemporal_load((const f32x4*)(x + idx + bj * HALF + 4));
;                     const f32x4 h0 = x0 + acc[ai][bj][m][0], h1v = x1 + acc[ai][bj][m][1];
;                     float f[8] = {h0[0], h0[1], h0[2], h0[3], h1v[0], h1v[1], h1v[2], h1v[3]};
; #pragma unroll
;                     for (int e = 0; e < 8; ++e) ss += f[e] * f[e];
;                     *(u32x4*)(h1b + idx + bj * HALF) = pack8(f); }
;                 ss += __shfl_xor(ss, 16); ss += __shfl_xor(ss, 32);
;                 if (fq == 0) atomicAdd(ssq + row, ss); }
	v_pk_add_f32 v[68:69], v[68:69], v[218:219]
	v_pk_add_f32 v[70:71], v[70:71], v[220:221]
	v_pk_add_f32 v[64:65], v[64:65], v[230:231]
	v_pk_add_f32 v[66:67], v[66:67], v[232:233]
	v_cvt_pk_bf16_f32 v210, v76, v77
	v_cvt_pk_bf16_f32 v211, v78, v79
	v_cvt_pk_bf16_f32 v212, v72, v73
	v_cvt_pk_bf16_f32 v213, v74, v75
	v_cvt_pk_bf16_f32 v218, v68, v69
	v_cvt_pk_bf16_f32 v219, v70, v71
	v_cvt_pk_bf16_f32 v220, v64, v65
	v_cvt_pk_bf16_f32 v221, v66, v67
	ds_write_b128 v234, v[210:213]
	ds_read_b128 v[210:213], v235
	ds_write_b128 v234, v[218:221]
	ds_read_b128 v[218:221], v235
	v_mul_f32_e32 v205, v76, v76
	v_fmac_f32_e32 v205, v77, v77
	v_fmac_f32_e32 v205, v78, v78
	v_fmac_f32_e32 v205, v79, v79
	v_fmac_f32_e32 v205, v72, v72
	v_fmac_f32_e32 v205, v73, v73
	v_fmac_f32_e32 v205, v74, v74
	v_fmac_f32_e32 v205, v75, v75
	v_fmac_f32_e32 v205, v68, v68
	v_fmac_f32_e32 v205, v69, v69
	v_fmac_f32_e32 v205, v70, v70
	v_fmac_f32_e32 v205, v71, v71
	v_fmac_f32_e32 v205, v64, v64
	v_fmac_f32_e32 v205, v65, v65
	v_fmac_f32_e32 v205, v66, v66
	v_fmac_f32_e32 v205, v67, v67
	s_waitcnt lgkmcnt(2)
	global_store_dwordx4 v145, v[210:213], s[8:9]
	s_waitcnt lgkmcnt(0)
	global_store_dwordx4 v145, v[218:221], s[8:9] offset:256
	v_add_u32_e32 v145, 0x28000, v145
	global_load_dwordx4 v[210:213], v147, s[52:53]
	global_load_dwordx4 v[214:217], v144, s[52:53]
	global_load_dwordx4 v[218:221], v147, s[52:53] offset:512
	global_load_dwordx4 v[222:225], v144, s[52:53] offset:512
	s_waitcnt vmcnt(18)
	ds_write_b128 v226, v[158:161]
	s_mov_b64 exec, s[98:99]
	ds_read_b128 v[158:161], v227
	ds_read_b128 v[230:233], v228
	s_mov_b64 exec, -1
	ds_write_b128 v226, v[162:165]
	s_mov_b64 exec, s[100:101]
	ds_read_b128 v[158:161], v227
	ds_read_b128 v[230:233], v228
	s_mov_b64 exec, -1
	s_waitcnt lgkmcnt(0)
	v_pk_add_f32 v[60:61], v[60:61], v[158:159]
	v_pk_add_f32 v[62:63], v[62:63], v[160:161]
	v_pk_add_f32 v[56:57], v[56:57], v[230:231]
	v_pk_add_f32 v[58:59], v[58:59], v[232:233]
	ds_write_b128 v226, v[166:169]
	s_mov_b64 exec, s[98:99]
	ds_read_b128 v[166:169], v227
	ds_read_b128 v[230:233], v228
	s_mov_b64 exec, -1
	ds_write_b128 v226, v[170:173]
	s_mov_b64 exec, s[100:101]
	ds_read_b128 v[166:169], v227
	ds_read_b128 v[230:233], v228
	s_mov_b64 exec, -1
	s_waitcnt lgkmcnt(0)
	v_pk_add_f32 v[52:53], v[52:53], v[166:167]
	v_pk_add_f32 v[54:55], v[54:55], v[168:169]
	v_pk_add_f32 v[48:49], v[48:49], v[230:231]
	v_pk_add_f32 v[50:51], v[50:51], v[232:233]
	v_cvt_pk_bf16_f32 v158, v60, v61
	v_cvt_pk_bf16_f32 v159, v62, v63
	v_cvt_pk_bf16_f32 v160, v56, v57
	v_cvt_pk_bf16_f32 v161, v58, v59
	v_cvt_pk_bf16_f32 v166, v52, v53
	v_cvt_pk_bf16_f32 v167, v54, v55
	v_cvt_pk_bf16_f32 v168, v48, v49
	v_cvt_pk_bf16_f32 v169, v50, v51
	ds_write_b128 v234, v[158:161]
	ds_read_b128 v[158:161], v235
	ds_write_b128 v234, v[166:169]
	ds_read_b128 v[166:169], v235
	v_mul_f32_e32 v242, v60, v60
	v_fmac_f32_e32 v242, v61, v61
	v_fmac_f32_e32 v242, v62, v62
	v_fmac_f32_e32 v242, v63, v63
	v_fmac_f32_e32 v242, v56, v56
	v_fmac_f32_e32 v242, v57, v57
	v_fmac_f32_e32 v242, v58, v58
	v_fmac_f32_e32 v242, v59, v59
	v_fmac_f32_e32 v242, v52, v52
	v_fmac_f32_e32 v242, v53, v53
	v_fmac_f32_e32 v242, v54, v54
	v_fmac_f32_e32 v242, v55, v55
	v_fmac_f32_e32 v242, v48, v48
	v_fmac_f32_e32 v242, v49, v49
	v_fmac_f32_e32 v242, v50, v50
	v_fmac_f32_e32 v242, v51, v51
	s_waitcnt lgkmcnt(2)
	global_store_dwordx4 v145, v[158:161], s[8:9]
	s_waitcnt lgkmcnt(0)
	global_store_dwordx4 v145, v[166:169], s[8:9] offset:256
	v_add_u32_e32 v145, 0x8000, v145
	s_waitcnt vmcnt(14)
	ds_write_b128 v226, v[174:177]
	s_mov_b64 exec, s[98:99]
	ds_read_b128 v[174:177], v227
	ds_read_b128 v[230:233], v228
	s_mov_b64 exec, -1
	ds_write_b128 v226, v[178:181]
	s_mov_b64 exec, s[100:101]
	ds_read_b128 v[174:177], v227
	ds_read_b128 v[230:233], v228
	s_mov_b64 exec, -1
	s_waitcnt lgkmcnt(0)
	v_pk_add_f32 v[44:45], v[44:45], v[174:175]
	v_pk_add_f32 v[46:47], v[46:47], v[176:177]
	v_pk_add_f32 v[40:41], v[40:41], v[230:231]
	v_pk_add_f32 v[42:43], v[42:43], v[232:233]
	ds_write_b128 v226, v[182:185]
	s_mov_b64 exec, s[98:99]
	ds_read_b128 v[182:185], v227
	ds_read_b128 v[230:233], v228
	s_mov_b64 exec, -1
	ds_write_b128 v226, v[186:189]
	s_mov_b64 exec, s[100:101]
	ds_read_b128 v[182:185], v227
	ds_read_b128 v[230:233], v228
	s_mov_b64 exec, -1
	s_waitcnt lgkmcnt(0)
	v_pk_add_f32 v[36:37], v[36:37], v[182:183]
	v_pk_add_f32 v[38:39], v[38:39], v[184:185]
	v_pk_add_f32 v[32:33], v[32:33], v[230:231]
	v_pk_add_f32 v[34:35], v[34:35], v[232:233]
	v_cvt_pk_bf16_f32 v174, v44, v45
	v_cvt_pk_bf16_f32 v175, v46, v47
	v_cvt_pk_bf16_f32 v176, v40, v41
	v_cvt_pk_bf16_f32 v177, v42, v43
	v_cvt_pk_bf16_f32 v182, v36, v37
	v_cvt_pk_bf16_f32 v183, v38, v39
	v_cvt_pk_bf16_f32 v184, v32, v33
	v_cvt_pk_bf16_f32 v185, v34, v35
	ds_write_b128 v234, v[174:177]
	ds_read_b128 v[174:177], v235
	ds_write_b128 v234, v[182:185]
	ds_read_b128 v[182:185], v235
	v_mul_f32_e32 v243, v44, v44
	v_fmac_f32_e32 v243, v45, v45
	v_fmac_f32_e32 v243, v46, v46
	v_fmac_f32_e32 v243, v47, v47
	v_fmac_f32_e32 v243, v40, v40
	v_fmac_f32_e32 v243, v41, v41
	v_fmac_f32_e32 v243, v42, v42
	v_fmac_f32_e32 v243, v43, v43
	v_fmac_f32_e32 v243, v36, v36
	v_fmac_f32_e32 v243, v37, v37
	v_fmac_f32_e32 v243, v38, v38
	v_fmac_f32_e32 v243, v39, v39
	v_fmac_f32_e32 v243, v32, v32
	v_fmac_f32_e32 v243, v33, v33
	v_fmac_f32_e32 v243, v34, v34
	v_fmac_f32_e32 v243, v35, v35
	s_waitcnt lgkmcnt(2)
	global_store_dwordx4 v145, v[174:177], s[8:9]
	s_waitcnt lgkmcnt(0)
	global_store_dwordx4 v145, v[182:185], s[8:9] offset:256
	v_add_u32_e32 v145, 0x8000, v145
	s_waitcnt vmcnt(10)
; __device__ __forceinline__ u32x4 pack8(const float (&f)[8]) { u32x4 w; w.x = cvt_pk_bf16(f[0], f[1]); w.y = cvt_pk_bf16(f[2], f[3]); w.z = cvt_pk_bf16(f[4], f[5]); w.w = cvt_pk_bf16(f[6], f[7]); return w; }
;     __device__ __forceinline__ void operator()(const f32x4 (&acc)[2][2][4][2], const Unit& u, int wr, int wc, int fr, int fq) const {
;         const int row0 = u.pm * BM + wr * 64 + fr, col0 = u.pn * BM + wc * 32 + 8 * fq;
; #pragma unroll
;         for (int ai = 0; ai < 2; ++ai)
; #pragma unroll
;             for (int m = 0; m < 4; ++m) { const int row = row0 + ai * HALF + m * 16; const size_t idx = (size_t)row * 1024 + col0; float ss = 0.f;
; #pragma unroll
;                 for (int bj = 0; bj < 2; ++bj) { const f32x4 x0 = __builtin_nontemporal_load((const f32x4*)(x + idx + bj * HALF)), x1 = __builtin_nontemporal_load((const f32x4*)(x + idx + bj * HALF + 4));
;                     const f32x4 h0 = x0 + acc[ai][bj][m][0], h1v = x1 + acc[ai][bj][m][1];
;                     float f[8] = {h0[0], h0[1], h0[2], h0[3], h1v[0], h1v[1], h1v[2], h1v[3]};
; #pragma unroll
;                     for (int e = 0; e < 8; ++e) ss += f[e] * f[e];
;                     *(u32x4*)(h1b + idx + bj * HALF) = pack8(f); }
;                 ss += __shfl_xor(ss, 16); ss += __shfl_xor(ss, 32);
;                 if (fq == 0) atomicAdd(ssq + row, ss); }
	ds_write_b128 v226, v[190:193]
	s_mov_b64 exec, s[98:99]
	ds_read_b128 v[190:193], v227
	ds_read_b128 v[230:233], v228
	s_mov_b64 exec, -1
	ds_write_b128 v226, v[194:197]
	s_mov_b64 exec, s[100:101]
	ds_read_b128 v[190:193], v227
	ds_read_b128 v[230:233], v228
	s_mov_b64 exec, -1
	s_waitcnt lgkmcnt(0)
	v_pk_add_f32 v[28:29], v[28:29], v[190:191]
	v_pk_add_f32 v[30:31], v[30:31], v[192:193]
	v_pk_add_f32 v[24:25], v[24:25], v[230:231]
	v_pk_add_f32 v[26:27], v[26:27], v[232:233]
	ds_write_b128 v226, v[198:201]
	s_mov_b64 exec, s[98:99]
	ds_read_b128 v[198:201], v227
	ds_read_b128 v[230:233], v228
	s_mov_b64 exec, -1
	ds_write_b128 v226, v[206:209]
	s_mov_b64 exec, s[100:101]
	ds_read_b128 v[198:201], v227
	ds_read_b128 v[230:233], v228
	s_mov_b64 exec, -1
	s_waitcnt lgkmcnt(0)
	v_pk_add_f32 v[20:21], v[20:21], v[198:199]
	v_pk_add_f32 v[22:23], v[22:23], v[200:201]
	v_pk_add_f32 v[16:17], v[16:17], v[230:231]
	v_pk_add_f32 v[18:19], v[18:19], v[232:233]
	v_cvt_pk_bf16_f32 v190, v28, v29
	v_cvt_pk_bf16_f32 v191, v30, v31
	v_cvt_pk_bf16_f32 v192, v24, v25
	v_cvt_pk_bf16_f32 v193, v26, v27
	v_cvt_pk_bf16_f32 v198, v20, v21
	v_cvt_pk_bf16_f32 v199, v22, v23
	v_cvt_pk_bf16_f32 v200, v16, v17
	v_cvt_pk_bf16_f32 v201, v18, v19
	ds_write_b128 v234, v[190:193]
	ds_read_b128 v[190:193], v235
	ds_write_b128 v234, v[198:201]
	ds_read_b128 v[198:201], v235
	v_mul_f32_e32 v244, v28, v28
	v_fmac_f32_e32 v244, v29, v29
	v_fmac_f32_e32 v244, v30, v30
	v_fmac_f32_e32 v244, v31, v31
	v_fmac_f32_e32 v244, v24, v24
	v_fmac_f32_e32 v244, v25, v25
	v_fmac_f32_e32 v244, v26, v26
	v_fmac_f32_e32 v244, v27, v27
	v_fmac_f32_e32 v244, v20, v20
	v_fmac_f32_e32 v244, v21, v21
	v_fmac_f32_e32 v244, v22, v22
	v_fmac_f32_e32 v244, v23, v23
	v_fmac_f32_e32 v244, v16, v16
	v_fmac_f32_e32 v244, v17, v17
	v_fmac_f32_e32 v244, v18, v18
	v_fmac_f32_e32 v244, v19, v19
	s_waitcnt lgkmcnt(2)
	global_store_dwordx4 v145, v[190:193], s[8:9]
	s_waitcnt lgkmcnt(0)
	global_store_dwordx4 v145, v[198:201], s[8:9] offset:256
	v_add_u32_e32 v145, 0x8000, v145
	s_waitcnt vmcnt(6)
	ds_write_b128 v226, v[210:213]
	s_mov_b64 exec, s[98:99]
	ds_read_b128 v[210:213], v227
	ds_read_b128 v[230:233], v228
	s_mov_b64 exec, -1
	ds_write_b128 v226, v[214:217]
	s_mov_b64 exec, s[100:101]
	ds_read_b128 v[210:213], v227
	ds_read_b128 v[230:233], v228
	s_mov_b64 exec, -1
	s_waitcnt lgkmcnt(0)
	v_pk_add_f32 v[12:13], v[12:13], v[210:211]
	v_pk_add_f32 v[14:15], v[14:15], v[212:213]
	v_pk_add_f32 v[8:9], v[8:9], v[230:231]
	v_pk_add_f32 v[10:11], v[10:11], v[232:233]
	ds_write_b128 v226, v[218:221]
	s_mov_b64 exec, s[98:99]
	ds_read_b128 v[218:221], v227
	ds_read_b128 v[230:233], v228
	s_mov_b64 exec, -1
	ds_write_b128 v226, v[222:225]
	s_mov_b64 exec, s[100:101]
	ds_read_b128 v[218:221], v227
	ds_read_b128 v[230:233], v228
	s_mov_b64 exec, -1
	s_waitcnt lgkmcnt(0)
	v_pk_add_f32 v[4:5], v[4:5], v[218:219]
	v_pk_add_f32 v[6:7], v[6:7], v[220:221]
	v_pk_add_f32 v[0:1], v[0:1], v[230:231]
	v_pk_add_f32 v[2:3], v[2:3], v[232:233]
	v_cvt_pk_bf16_f32 v210, v12, v13
	v_cvt_pk_bf16_f32 v211, v14, v15
	v_cvt_pk_bf16_f32 v212, v8, v9
	v_cvt_pk_bf16_f32 v213, v10, v11
	v_cvt_pk_bf16_f32 v218, v4, v5
	v_cvt_pk_bf16_f32 v219, v6, v7
	v_cvt_pk_bf16_f32 v220, v0, v1
	v_cvt_pk_bf16_f32 v221, v2, v3
	ds_write_b128 v234, v[210:213]
	ds_read_b128 v[210:213], v235
	ds_write_b128 v234, v[218:221]
	ds_read_b128 v[218:221], v235
	v_mul_f32_e32 v245, v12, v12
	v_fmac_f32_e32 v245, v13, v13
	v_fmac_f32_e32 v245, v14, v14
	v_fmac_f32_e32 v245, v15, v15
	v_fmac_f32_e32 v245, v8, v8
	v_fmac_f32_e32 v245, v9, v9
	v_fmac_f32_e32 v245, v10, v10
	v_fmac_f32_e32 v245, v11, v11
	v_fmac_f32_e32 v245, v4, v4
	v_fmac_f32_e32 v245, v5, v5
	v_fmac_f32_e32 v245, v6, v6
	v_fmac_f32_e32 v245, v7, v7
	v_fmac_f32_e32 v245, v0, v0
	v_fmac_f32_e32 v245, v1, v1
	v_fmac_f32_e32 v245, v2, v2
	v_fmac_f32_e32 v245, v3, v3
	s_waitcnt lgkmcnt(2)
	global_store_dwordx4 v145, v[210:213], s[8:9]
	s_waitcnt lgkmcnt(0)
	global_store_dwordx4 v145, v[218:221], s[8:9] offset:256
	v_xor_b32_e32 v158, 16, v156
	v_xor_b32_e32 v159, 32, v156
	v_lshlrev_b32_e32 v158, 2, v158
	v_lshlrev_b32_e32 v159, 2, v159
	ds_bpermute_b32 v162, v158, v157
	ds_bpermute_b32 v163, v158, v202
	ds_bpermute_b32 v164, v158, v203
	ds_bpermute_b32 v165, v158, v205
	ds_bpermute_b32 v166, v158, v242
	ds_bpermute_b32 v167, v158, v243
	ds_bpermute_b32 v168, v158, v244
	ds_bpermute_b32 v169, v158, v245
	s_waitcnt lgkmcnt(0)
	v_add_f32_e32 v157, v157, v162
	v_add_f32_e32 v202, v202, v163
	v_add_f32_e32 v203, v203, v164
	v_add_f32_e32 v205, v205, v165
	v_add_f32_e32 v242, v242, v166
	v_add_f32_e32 v243, v243, v167
	v_add_f32_e32 v244, v244, v168
	v_add_f32_e32 v245, v245, v169
	ds_bpermute_b32 v162, v159, v157
	ds_bpermute_b32 v163, v159, v202
	ds_bpermute_b32 v164, v159, v203
	ds_bpermute_b32 v165, v159, v205
	ds_bpermute_b32 v166, v159, v242
	ds_bpermute_b32 v167, v159, v243
	ds_bpermute_b32 v168, v159, v244
	ds_bpermute_b32 v169, v159, v245
	s_waitcnt lgkmcnt(0)
	v_add_f32_e32 v157, v157, v162
	v_add_f32_e32 v202, v202, v163
	v_add_f32_e32 v203, v203, v164
	v_add_f32_e32 v205, v205, v165
	v_add_f32_e32 v242, v242, v166
	v_add_f32_e32 v243, v243, v167
	v_add_f32_e32 v244, v244, v168
	v_add_f32_e32 v245, v245, v169
	s_and_saveexec_b64 s[44:45], s[4:5]
	global_atomic_add_f32 v149, v157, s[68:69]
	global_atomic_add_f32 v149, v202, s[68:69] offset:64
	global_atomic_add_f32 v149, v203, s[68:69] offset:128
	global_atomic_add_f32 v149, v205, s[68:69] offset:192
	global_atomic_add_f32 v149, v242, s[68:69] offset:512
	global_atomic_add_f32 v149, v243, s[68:69] offset:576
	global_atomic_add_f32 v149, v244, s[68:69] offset:640
	global_atomic_add_f32 v149, v245, s[68:69] offset:704
	s_or_b64 exec, exec, s[44:45]
	s_andn2_b64 vcc, exec, s[6:7]
	s_mov_b64 s[6:7], -1
	s_cbranch_vccnz .LBB0_637
	s_andn2_b64 vcc, exec, s[12:13]
	s_cbranch_vccnz .LBB0_636
	s_barrier
	s_branch .LBB0_636
